# v37 + phase-0 silu staging loop with 8 loads in flight per iteration instead of 48 dependent load/wait iterations
# speedup vs baseline: 1.0041x; 1.0041x over previous
; __device__ __forceinline__ float silu(float g) { return g / (1.0f + __expf(-g)); }
; __device__ __forceinline__ void phase_mod(const Params& p, LAS unsigned char* lds, const int tid) {
;     ...
;     for (int e = tid; e < 24 * 1024; e += 512) {
;         const int b = e >> 10, k = e & 1023;
;         const float c = b < 16 ? p.cp[b * 1024 + k] : p.cs[(b - 16) * 1024 + k];
;         sc[k * 24 + b] = silu(c);
;     }
.LBB0_514:
	s_or_b64 exec, exec, s[28:29]
	s_movk_i32 s0, 0x6000
	v_cmp_gt_i32_e32 vcc, s0, v174
	s_and_saveexec_b64 s[28:29], vcc
	s_cbranch_execz .LBB0_519
	v_ashrrev_i32_e32 v175, 31, v174
	s_waitcnt lgkmcnt(0)
	v_lshlrev_b32_e32 v0, 2, v174
	v_mul_u32_u24_e32 v3, 0x60, v174
	s_mov_b32 s30, 0
.Lstg_loop:
	s_cmp_lt_u32 s30, 4
	s_cselect_b32 s0, s72, s74
	s_cselect_b32 s1, s73, s75
	s_and_b32 s31, s30, 3
	s_lshl_b32 s31, s31, 14
	s_add_u32 s0, s0, s31
	s_addc_u32 s1, s1, 0
	global_load_dword v8, v0, s[0:1]
	global_load_dword v9, v0, s[0:1] offset:2048
	s_add_u32 s0, s0, 0x1000
	s_addc_u32 s1, s1, 0
	global_load_dword v10, v0, s[0:1]
	global_load_dword v11, v0, s[0:1] offset:2048
	s_add_u32 s0, s0, 0x1000
	s_addc_u32 s1, s1, 0
	global_load_dword v12, v0, s[0:1]
	global_load_dword v13, v0, s[0:1] offset:2048
	s_add_u32 s0, s0, 0x1000
	s_addc_u32 s1, s1, 0
	global_load_dword v14, v0, s[0:1]
	global_load_dword v15, v0, s[0:1] offset:2048
	s_waitcnt vmcnt(0)
	v_mul_f32_e32 v20, 0xbfb8aa3b, v8
	v_exp_f32_e32 v20, v20
	s_nop 0
	v_add_f32_e32 v21, 1.0, v20
	v_div_scale_f32 v22, s[0:1], v21, v21, v8
	v_rcp_f32_e32 v20, v22
	v_div_scale_f32 v23, vcc, v8, v21, v8
	v_fma_f32 v24, -v22, v20, 1.0
	v_fmac_f32_e32 v20, v24, v20
	v_mul_f32_e32 v24, v23, v20
	v_fma_f32 v25, -v22, v24, v23
	v_fmac_f32_e32 v24, v25, v20
	v_fma_f32 v22, -v22, v24, v23
	v_div_fmas_f32 v22, v22, v20, v24
	v_div_fixup_f32 v8, v22, v21, v8
	v_mul_f32_e32 v20, 0xbfb8aa3b, v9
	v_exp_f32_e32 v20, v20
	s_nop 0
	v_add_f32_e32 v21, 1.0, v20
	v_div_scale_f32 v22, s[0:1], v21, v21, v9
	v_rcp_f32_e32 v20, v22
	v_div_scale_f32 v23, vcc, v9, v21, v9
	v_fma_f32 v24, -v22, v20, 1.0
	v_fmac_f32_e32 v20, v24, v20
	v_mul_f32_e32 v24, v23, v20
	v_fma_f32 v25, -v22, v24, v23
	v_fmac_f32_e32 v24, v25, v20
	v_fma_f32 v22, -v22, v24, v23
	v_div_fmas_f32 v22, v22, v20, v24
	v_div_fixup_f32 v9, v22, v21, v9
	v_mul_f32_e32 v20, 0xbfb8aa3b, v10
	v_exp_f32_e32 v20, v20
	s_nop 0
	v_add_f32_e32 v21, 1.0, v20
	v_div_scale_f32 v22, s[0:1], v21, v21, v10
	v_rcp_f32_e32 v20, v22
	v_div_scale_f32 v23, vcc, v10, v21, v10
	v_fma_f32 v24, -v22, v20, 1.0
	v_fmac_f32_e32 v20, v24, v20
	v_mul_f32_e32 v24, v23, v20
	v_fma_f32 v25, -v22, v24, v23
	v_fmac_f32_e32 v24, v25, v20
	v_fma_f32 v22, -v22, v24, v23
	v_div_fmas_f32 v22, v22, v20, v24
	v_div_fixup_f32 v10, v22, v21, v10
	v_mul_f32_e32 v20, 0xbfb8aa3b, v11
	v_exp_f32_e32 v20, v20
	s_nop 0
	v_add_f32_e32 v21, 1.0, v20
	v_div_scale_f32 v22, s[0:1], v21, v21, v11
	v_rcp_f32_e32 v20, v22
	v_div_scale_f32 v23, vcc, v11, v21, v11
	v_fma_f32 v24, -v22, v20, 1.0
	v_fmac_f32_e32 v20, v24, v20
	v_mul_f32_e32 v24, v23, v20
	v_fma_f32 v25, -v22, v24, v23
	v_fmac_f32_e32 v24, v25, v20
	v_fma_f32 v22, -v22, v24, v23
	v_div_fmas_f32 v22, v22, v20, v24
	v_div_fixup_f32 v11, v22, v21, v11
	v_mul_f32_e32 v20, 0xbfb8aa3b, v12
	v_exp_f32_e32 v20, v20
	s_nop 0
	v_add_f32_e32 v21, 1.0, v20
	v_div_scale_f32 v22, s[0:1], v21, v21, v12
	v_rcp_f32_e32 v20, v22
	v_div_scale_f32 v23, vcc, v12, v21, v12
	v_fma_f32 v24, -v22, v20, 1.0
	v_fmac_f32_e32 v20, v24, v20
	v_mul_f32_e32 v24, v23, v20
	v_fma_f32 v25, -v22, v24, v23
	v_fmac_f32_e32 v24, v25, v20
	v_fma_f32 v22, -v22, v24, v23
	v_div_fmas_f32 v22, v22, v20, v24
	v_div_fixup_f32 v12, v22, v21, v12
	v_mul_f32_e32 v20, 0xbfb8aa3b, v13
	v_exp_f32_e32 v20, v20
	s_nop 0
	v_add_f32_e32 v21, 1.0, v20
	v_div_scale_f32 v22, s[0:1], v21, v21, v13
	v_rcp_f32_e32 v20, v22
	v_div_scale_f32 v23, vcc, v13, v21, v13
	v_fma_f32 v24, -v22, v20, 1.0
	v_fmac_f32_e32 v20, v24, v20
	v_mul_f32_e32 v24, v23, v20
	v_fma_f32 v25, -v22, v24, v23
	v_fmac_f32_e32 v24, v25, v20
	v_fma_f32 v22, -v22, v24, v23
	v_div_fmas_f32 v22, v22, v20, v24
	v_div_fixup_f32 v13, v22, v21, v13
	v_mul_f32_e32 v20, 0xbfb8aa3b, v14
	v_exp_f32_e32 v20, v20
	s_nop 0
	v_add_f32_e32 v21, 1.0, v20
	v_div_scale_f32 v22, s[0:1], v21, v21, v14
	v_rcp_f32_e32 v20, v22
	v_div_scale_f32 v23, vcc, v14, v21, v14
	v_fma_f32 v24, -v22, v20, 1.0
	v_fmac_f32_e32 v20, v24, v20
	v_mul_f32_e32 v24, v23, v20
	v_fma_f32 v25, -v22, v24, v23
	v_fmac_f32_e32 v24, v25, v20
	v_fma_f32 v22, -v22, v24, v23
	v_div_fmas_f32 v22, v22, v20, v24
	v_div_fixup_f32 v14, v22, v21, v14
	v_mul_f32_e32 v20, 0xbfb8aa3b, v15
	v_exp_f32_e32 v20, v20
	s_nop 0
	v_add_f32_e32 v21, 1.0, v20
	v_div_scale_f32 v22, s[0:1], v21, v21, v15
	v_rcp_f32_e32 v20, v22
	v_div_scale_f32 v23, vcc, v15, v21, v15
	v_fma_f32 v24, -v22, v20, 1.0
	v_fmac_f32_e32 v20, v24, v20
	v_mul_f32_e32 v24, v23, v20
	v_fma_f32 v25, -v22, v24, v23
	v_fmac_f32_e32 v24, v25, v20
	v_fma_f32 v22, -v22, v24, v23
	v_div_fmas_f32 v22, v22, v20, v24
	v_div_fixup_f32 v15, v22, v21, v15
	ds_write_b32 v3, v8
	ds_write_b32 v3, v9 offset:49152
	ds_write_b32 v3, v10 offset:4
	ds_write_b32 v3, v11 offset:49156
	ds_write_b32 v3, v12 offset:8
	ds_write_b32 v3, v13 offset:49160
	ds_write_b32 v3, v14 offset:12
	ds_write_b32 v3, v15 offset:49164
	v_add_u32_e32 v3, 16, v3
	s_add_i32 s30, s30, 1
	s_cmp_lt_u32 s30, 6
	s_cbranch_scc1 .Lstg_loop
